# B2 (decay/a/kk elementwise) rewritten as 8 interleaved streams with SGPR-free cross-lane sums; relaxed two vmcnt waits in the scan chunk loop
# speedup vs baseline: 1.0085x; 1.0085x over previous
;     ...
;   for (int ch = -1; ch < 72; ++ch) {
;     const int nx = ch + 1;
;     const bool more = nx < 72;
;     if (more) {
;       const int n0 = nx * 32; const bool cx = n0 < 256;
;       const int tlo = dir ? (cx ? 224 - n0 : 2528 - n0) : n0;
;       const int slo = cx ? 0 : 256, shi = cx ? 256 : 2304;
;       rg0 = *(const uint4*)(pb + (size_t)(tlo + (tid >> 5)) * INW);
;       rg1 = *(const uint4*)(pb + (size_t)(tlo + (tid >> 5) + 8) * INW);
;       rg2 = *(const uint4*)(pb + (size_t)(tlo + (tid >> 5) + 16) * INW);
;       rg3 = *(const uint4*)(pb + (size_t)(tlo + (tid >> 5) + 24) * INW);
;       rg4 = make_uint4(0, 0, 0, 0);
;       if (tid < 64) { const int tok = (tid >> 5) ? tlo + 32 : tlo - 1; if (tok >= slo && tok < shi) rg4 = *(const uint4*)(pb + (size_t)tok * INW); }
;     }
.LBB0_351:
	s_add_i32 s90, s91, 1
	s_cmpk_lg_i32 s91, 0x47
	s_cselect_b64 s[34:35], -1, 0
	s_cmpk_eq_i32 s91, 0x47
	s_cbranch_scc1 .LBB0_357
	s_lshl_b32 s92, s90, 5
	s_cmp_lt_i32 s91, 7
	s_cselect_b64 s[12:13], -1, 0
	s_and_b64 s[76:77], s[12:13], exec
	s_movk_i32 s16, 0x9e0
	s_cselect_b32 s76, 0xe0, s16
	s_sub_i32 s93, s76, s92
	s_and_b64 s[76:77], s[4:5], exec
	s_cselect_b32 s92, s92, s93
	v_add_u32_e32 v4, s92, v132
	s_movk_i32 s16, 0x1980
	v_mad_i64_i32 v[0:1], s[76:77], v4, s16, v[110:111]
	v_add_u32_e32 v2, 8, v4
	v_mad_i64_i32 v[2:3], s[76:77], v2, s16, v[110:111]
	global_load_dwordx4 v[24:27], v[0:1], off
	global_load_dwordx4 v[28:31], v[2:3], off
	v_add_u32_e32 v0, 16, v4
	v_mad_i64_i32 v[0:1], s[76:77], v0, s16, v[110:111]
	v_add_u32_e32 v2, 24, v4
	v_mad_i64_i32 v[2:3], s[76:77], v2, s16, v[110:111]
	global_load_dwordx4 v[32:35], v[0:1], off
	global_load_dwordx4 v[36:39], v[2:3], off
	v_mov_b32_e32 v43, 0
	v_mov_b32_e32 v42, 0
	v_mov_b32_e32 v41, 0
	v_mov_b32_e32 v40, 0
	s_and_saveexec_b64 s[76:77], s[0:1]
	s_cbranch_execz .LBB0_356
	s_and_b64 s[12:13], s[12:13], exec
	s_movk_i32 s12, 0x100
	s_cselect_b32 s12, s12, 0x900
	s_cselect_b32 s13, 0, 0x100
	v_add_u32_e32 v0, s92, v129
	v_cmp_le_i32_e32 vcc, s13, v0
	v_cmp_gt_i32_e64 s[12:13], s12, v0
	s_and_b64 s[92:93], vcc, s[12:13]
	v_mov_b32_e32 v43, 0
	v_mov_b32_e32 v42, 0
	v_mov_b32_e32 v41, 0
	v_mov_b32_e32 v40, 0
	s_and_saveexec_b64 s[12:13], s[92:93]
	s_cbranch_execz .LBB0_355
	v_mad_u64_u32 v[0:1], s[92:93], v0, s16, v[110:111]
	global_load_dwordx4 v[40:43], v[0:1], off

; DI float bf2f(u16 v) { return __uint_as_float(((unsigned)v) << 16); }
;     ...
;     if (more) {
;       *(uint4*)(raw + (1 + (tid >> 5)) * 256 + vec * 8) = rg0;
;       *(uint4*)(raw + (9 + (tid >> 5)) * 256 + vec * 8) = rg1;
;       *(uint4*)(raw + (17 + (tid >> 5)) * 256 + vec * 8) = rg2;
;       *(uint4*)(raw + (25 + (tid >> 5)) * 256 + vec * 8) = rg3;
;       if (tid < 64) *(uint4*)(raw + ((tid >> 5) ? 33 : 0) * 256 + vec * 8) = rg4;
;       __syncthreads();
;       if (!(pm & 2)) {
;         float pv[34];
; #pragma unroll
;         for (int j = 0; j < 34; ++j) pv[j] = bf2f(raw[j * 256 + c]);
;         if (wv < 3) {
;           float* pdst = prep + (wv == 0 ? 256 + c : (wv == 1 ? 192 + (c - 64) : 320 + (c - 128)));
; #pragma unroll
;           for (int j = 0; j < 32; ++j) {
;             const float psv = pv[j + 1] + mu * (0.5f * (pv[j] + pv[j + 2]) - pv[j + 1]);
.LBB0_365:
	s_andn2_b64 vcc, exec, s[34:35]
	s_cbranch_vccnz .LBB0_350
	s_waitcnt vmcnt(3)
	ds_write_b128 v136, v[24:27] offset:49664
	s_waitcnt vmcnt(2)
	ds_write_b128 v136, v[28:31] offset:53760
	s_waitcnt vmcnt(1)
	ds_write_b128 v136, v[32:35] offset:57856
	s_waitcnt vmcnt(1)
	ds_write_b128 v136, v[36:39] offset:61952
	s_and_saveexec_b64 s[12:13], s[0:1]
	ds_write_b128 v137, v[40:43] offset:49152
	s_or_b64 exec, exec, s[12:13]
	s_waitcnt lgkmcnt(0)
	s_barrier
	ds_read_u16 v0, v138 offset:49152
	ds_read_u16 v1, v138 offset:49664
	ds_read_u16 v2, v138 offset:50176
	ds_read_u16 v3, v138 offset:50688
	ds_read_u16 v4, v138 offset:51200
	ds_read_u16 v5, v138 offset:51712
	ds_read_u16 v6, v138 offset:52224
	ds_read_u16 v7, v138 offset:52736
	s_waitcnt lgkmcnt(7)
	v_lshlrev_b32_e32 v60, 16, v0
	s_waitcnt lgkmcnt(6)
	v_lshlrev_b32_e32 v59, 16, v1
	s_waitcnt lgkmcnt(5)
	v_lshlrev_b32_e32 v58, 16, v2
	s_waitcnt lgkmcnt(4)
	v_lshlrev_b32_e32 v56, 16, v3
	s_waitcnt lgkmcnt(3)
	v_lshlrev_b32_e32 v54, 16, v4
	s_waitcnt lgkmcnt(2)
	v_lshlrev_b32_e32 v52, 16, v5
	s_waitcnt lgkmcnt(1)
	v_lshlrev_b32_e32 v49, 16, v6
	s_waitcnt lgkmcnt(0)
	v_lshlrev_b32_e32 v46, 16, v7
	ds_read_u16 v0, v138 offset:53248
	ds_read_u16 v1, v138 offset:53760
	ds_read_u16 v2, v138 offset:54272
	ds_read_u16 v3, v138 offset:54784
	ds_read_u16 v4, v138 offset:55296
	ds_read_u16 v5, v138 offset:55808
	ds_read_u16 v6, v138 offset:56320
	ds_read_u16 v7, v138 offset:56832
	s_waitcnt lgkmcnt(7)
	v_lshlrev_b32_e32 v57, 16, v0
	s_waitcnt lgkmcnt(6)
	v_lshlrev_b32_e32 v55, 16, v1
	s_waitcnt lgkmcnt(5)
	v_lshlrev_b32_e32 v53, 16, v2
	s_waitcnt lgkmcnt(4)
	v_lshlrev_b32_e32 v50, 16, v3
	s_waitcnt lgkmcnt(3)
	v_lshlrev_b32_e32 v47, 16, v4
	s_waitcnt lgkmcnt(2)
	v_lshlrev_b32_e32 v44, 16, v5
	s_waitcnt lgkmcnt(1)
	v_lshlrev_b32_e32 v13, 16, v6
	s_waitcnt lgkmcnt(0)
	v_lshlrev_b32_e32 v10, 16, v7
	ds_read_u16 v0, v138 offset:57344
	ds_read_u16 v1, v138 offset:57856
	ds_read_u16 v2, v138 offset:58368
	ds_read_u16 v3, v138 offset:58880
	ds_read_u16 v4, v138 offset:59392
	ds_read_u16 v5, v138 offset:59904
	ds_read_u16 v6, v138 offset:60416
	ds_read_u16 v7, v138 offset:60928
	s_waitcnt lgkmcnt(7)
	v_lshlrev_b32_e32 v51, 16, v0
	s_waitcnt lgkmcnt(6)
	v_lshlrev_b32_e32 v48, 16, v1
	s_waitcnt lgkmcnt(5)
	v_lshlrev_b32_e32 v45, 16, v2
	s_waitcnt lgkmcnt(3)
	v_lshlrev_b32_e32 v11, 16, v4
	s_waitcnt lgkmcnt(2)
	v_lshlrev_b32_e32 v8, 16, v5
	ds_read_u16 v0, v138 offset:61440
	ds_read_u16 v1, v138 offset:61952
	ds_read_u16 v2, v138 offset:62464
	ds_read_u16 v4, v138 offset:62976
	ds_read_u16 v5, v138 offset:63488
	ds_read_u16 v61, v138 offset:64000
	ds_read_u16 v62, v138 offset:64512
	ds_read_u16 v63, v138 offset:65024
	s_waitcnt lgkmcnt(7)
	v_lshlrev_b32_e32 v15, 16, v0
	ds_read_u16 v0, v139 offset:16384
	ds_read_u16 v64, v139 offset:16896
	v_lshlrev_b32_e32 v14, 16, v3
	v_lshlrev_b32_e32 v6, 16, v6
	v_lshlrev_b32_e32 v3, 16, v7
	s_waitcnt lgkmcnt(8)
	v_lshlrev_b32_e32 v12, 16, v1
	s_waitcnt lgkmcnt(7)
	v_lshlrev_b32_e32 v9, 16, v2
	s_waitcnt lgkmcnt(6)
	v_lshlrev_b32_e32 v7, 16, v4
	s_waitcnt lgkmcnt(5)
	v_lshlrev_b32_e32 v4, 16, v5
	s_waitcnt lgkmcnt(4)
	v_lshlrev_b32_e32 v5, 16, v61
	s_waitcnt lgkmcnt(3)
	v_lshlrev_b32_e32 v2, 16, v62
	s_waitcnt lgkmcnt(2)
	v_lshlrev_b32_e32 v1, 16, v63
	s_waitcnt lgkmcnt(1)
	v_lshlrev_b32_e32 v0, 16, v0
	s_waitcnt lgkmcnt(0)
	v_lshlrev_b32_e32 v61, 16, v64
	v_add_f32_e32 v60, v60, v58
	v_add_f32_e32 v62, v59, v56
	v_add_f32_e32 v63, v58, v54
	v_add_f32_e32 v64, v56, v52
	v_add_f32_e32 v65, v54, v49
	v_add_f32_e32 v66, v52, v46
	v_add_f32_e32 v67, v49, v57
	v_add_f32_e32 v68, v46, v55
	v_add_f32_e32 v69, v57, v53
	v_add_f32_e32 v70, v55, v50
	v_add_f32_e32 v71, v53, v47
	v_add_f32_e32 v72, v50, v44
	v_add_f32_e32 v73, v47, v13
	v_add_f32_e32 v74, v44, v10
	v_add_f32_e32 v75, v13, v51
	v_add_f32_e32 v76, v10, v48
	v_add_f32_e32 v92, v51, v45
	v_add_f32_e32 v93, v48, v14
	v_add_f32_e32 v94, v45, v11
	v_add_f32_e32 v95, v14, v8
	v_add_f32_e32 v96, v11, v6
	v_add_f32_e32 v98, v8, v3
	v_add_f32_e32 v99, v6, v15
	v_add_f32_e32 v100, v3, v12
	v_add_f32_e32 v101, v15, v9
	v_add_f32_e32 v102, v12, v7
	v_add_f32_e32 v103, v9, v4
	v_add_f32_e32 v104, v7, v5
	v_add_f32_e32 v105, v4, v2
	v_add_f32_e32 v106, v5, v1
	v_add_f32_e32 v107, v2, v0
	v_add_f32_e32 v108, v1, v61
	s_mov_b64 s[12:13], -1
	s_andn2_b64 vcc, exec, s[88:89]
	v_fma_f32 v91, v60, 0.5, -v59
	v_fma_f32 v90, v62, 0.5, -v58
	v_fma_f32 v89, v63, 0.5, -v56
	v_fma_f32 v88, v64, 0.5, -v54
	v_fma_f32 v87, v65, 0.5, -v52
	v_fma_f32 v86, v66, 0.5, -v49
	v_fma_f32 v85, v67, 0.5, -v46
	v_fma_f32 v84, v68, 0.5, -v57
	v_fma_f32 v83, v69, 0.5, -v55
	v_fma_f32 v82, v70, 0.5, -v53
	v_fma_f32 v81, v71, 0.5, -v50
	v_fma_f32 v80, v72, 0.5, -v47
	v_fma_f32 v79, v73, 0.5, -v44
	v_fma_f32 v78, v74, 0.5, -v13
	v_fma_f32 v77, v75, 0.5, -v10
	v_fma_f32 v76, v76, 0.5, -v51
	v_fma_f32 v75, v92, 0.5, -v48
	v_fma_f32 v74, v93, 0.5, -v45
	v_fma_f32 v73, v94, 0.5, -v14
	v_fma_f32 v72, v95, 0.5, -v11
	v_fma_f32 v71, v96, 0.5, -v8
	v_fma_f32 v70, v98, 0.5, -v6
	v_fma_f32 v69, v99, 0.5, -v3
	v_fma_f32 v68, v100, 0.5, -v15
	v_fma_f32 v67, v101, 0.5, -v12
	v_fma_f32 v66, v102, 0.5, -v9
	v_fma_f32 v65, v103, 0.5, -v7
	v_fma_f32 v64, v104, 0.5, -v4
	v_fma_f32 v63, v105, 0.5, -v5
	v_fma_f32 v62, v106, 0.5, -v2
	v_fma_f32 v61, v107, 0.5, -v1
	v_fma_f32 v60, v108, 0.5, -v0
	s_cbranch_vccnz .LBB0_370
; DI u16 f2bf(float x) { unsigned u = __float_as_uint(x); u += 0x7fffu + ((u >> 16) & 1u); return (u16)(u >> 16); }
;     ...
;           u16* tdst = ((c < 224) ? twb : tab) + ((c - 192) & 31);
; #pragma unroll
;           for (int j = 0; j < 32; ++j) {
;             const float psv = pv[j + 1] + mu * (0.5f * (pv[j] + pv[j + 2]) - pv[j + 1]);
;             const float th = 1.f - 2.f * __builtin_amdgcn_rcpf(__expf(2.f * psv) + 1.f);
;             tdst[(dir ? 31 - j : j) * 40] = f2bf((c < 224) ? th : psv);
;           }
	s_movk_i32 s12, 0x7fff
	v_fma_f32 v24, v123, v91, v59
	v_fma_f32 v26, v123, v90, v58
	v_fma_f32 v28, v123, v89, v56
	v_fma_f32 v30, v123, v88, v54
	v_fma_f32 v32, v123, v87, v52
	v_fma_f32 v34, v123, v86, v49
	v_fma_f32 v36, v123, v85, v46
	v_fma_f32 v38, v123, v84, v57
	v_add_f32_e32 v25, v24, v24
	v_add_f32_e32 v27, v26, v26
	v_add_f32_e32 v29, v28, v28
	v_add_f32_e32 v31, v30, v30
	v_add_f32_e32 v33, v32, v32
	v_add_f32_e32 v35, v34, v34
	v_add_f32_e32 v37, v36, v36
	v_add_f32_e32 v39, v38, v38
	v_mul_f32_e32 v25, 0x3fb8aa3b, v25
	v_mul_f32_e32 v27, 0x3fb8aa3b, v27
	v_mul_f32_e32 v29, 0x3fb8aa3b, v29
	v_mul_f32_e32 v31, 0x3fb8aa3b, v31
	v_mul_f32_e32 v33, 0x3fb8aa3b, v33
	v_mul_f32_e32 v35, 0x3fb8aa3b, v35
	v_mul_f32_e32 v37, 0x3fb8aa3b, v37
	v_mul_f32_e32 v39, 0x3fb8aa3b, v39
	v_exp_f32_e32 v25, v25
	v_exp_f32_e32 v27, v27
	v_exp_f32_e32 v29, v29
	v_exp_f32_e32 v31, v31
	v_exp_f32_e32 v33, v33
	v_exp_f32_e32 v35, v35
	v_exp_f32_e32 v37, v37
	v_exp_f32_e32 v39, v39
	v_add_f32_e32 v25, 1.0, v25
	v_add_f32_e32 v27, 1.0, v27
	v_add_f32_e32 v29, 1.0, v29
	v_add_f32_e32 v31, 1.0, v31
	v_add_f32_e32 v33, 1.0, v33
	v_add_f32_e32 v35, 1.0, v35
	v_add_f32_e32 v37, 1.0, v37
	v_add_f32_e32 v39, 1.0, v39
	v_rcp_f32_e32 v25, v25
	v_rcp_f32_e32 v27, v27
	v_rcp_f32_e32 v29, v29
	v_rcp_f32_e32 v31, v31
	v_rcp_f32_e32 v33, v33
	v_rcp_f32_e32 v35, v35
	v_rcp_f32_e32 v37, v37
	v_rcp_f32_e32 v39, v39
	v_fma_f32 v25, v25, -2.0, 1.0
	v_fma_f32 v27, v27, -2.0, 1.0
	v_fma_f32 v29, v29, -2.0, 1.0
	v_fma_f32 v31, v31, -2.0, 1.0
	v_fma_f32 v33, v33, -2.0, 1.0
	v_fma_f32 v35, v35, -2.0, 1.0
	v_fma_f32 v37, v37, -2.0, 1.0
	v_fma_f32 v39, v39, -2.0, 1.0
	v_cndmask_b32_e64 v24, v24, v25, s[6:7]
	v_cndmask_b32_e64 v26, v26, v27, s[6:7]
	v_cndmask_b32_e64 v28, v28, v29, s[6:7]
	v_cndmask_b32_e64 v30, v30, v31, s[6:7]
	v_cndmask_b32_e64 v32, v32, v33, s[6:7]
	v_cndmask_b32_e64 v34, v34, v35, s[6:7]
	v_cndmask_b32_e64 v36, v36, v37, s[6:7]
	v_cndmask_b32_e64 v38, v38, v39, s[6:7]
	v_bfe_u32 v25, v24, 16, 1
	v_bfe_u32 v27, v26, 16, 1
	v_bfe_u32 v29, v28, 16, 1
	v_bfe_u32 v31, v30, 16, 1
	v_bfe_u32 v33, v32, 16, 1
	v_bfe_u32 v35, v34, 16, 1
	v_bfe_u32 v37, v36, 16, 1
	v_bfe_u32 v39, v38, 16, 1
	v_add3_u32 v24, v24, v25, s12
	v_add3_u32 v26, v26, v27, s12
	v_add3_u32 v28, v28, v29, s12
	v_add3_u32 v30, v30, v31, s12
	v_add3_u32 v32, v32, v33, s12
	v_add3_u32 v34, v34, v35, s12
	v_add3_u32 v36, v36, v37, s12
	v_add3_u32 v38, v38, v39, s12
	v_add_u32_e32 v25, s95, v140
	v_add_u32_e32 v27, s97, v140
	v_add_u32_e32 v29, s28, v140
	v_add_u32_e32 v31, s29, v140
	v_add_u32_e32 v33, s17, v140
	v_add_u32_e32 v35, s18, v140
	v_add_u32_e32 v37, s19, v140
	v_add_u32_e32 v39, s20, v140
	ds_write_b16_d16_hi v25, v24
	ds_write_b16_d16_hi v27, v26
	ds_write_b16_d16_hi v29, v28
	ds_write_b16_d16_hi v31, v30
	ds_write_b16_d16_hi v33, v32
	ds_write_b16_d16_hi v35, v34
	ds_write_b16_d16_hi v37, v36
	ds_write_b16_d16_hi v39, v38
	v_fma_f32 v24, v123, v83, v55
	v_fma_f32 v26, v123, v82, v53
	v_fma_f32 v28, v123, v81, v50
	v_fma_f32 v30, v123, v80, v47
	v_fma_f32 v32, v123, v79, v44
	v_fma_f32 v34, v123, v78, v13
	v_fma_f32 v36, v123, v77, v10
	v_fma_f32 v38, v123, v76, v51
	v_add_f32_e32 v25, v24, v24
	v_add_f32_e32 v27, v26, v26
	v_add_f32_e32 v29, v28, v28
	v_add_f32_e32 v31, v30, v30
	v_add_f32_e32 v33, v32, v32
	v_add_f32_e32 v35, v34, v34
	v_add_f32_e32 v37, v36, v36
	v_add_f32_e32 v39, v38, v38
	v_mul_f32_e32 v25, 0x3fb8aa3b, v25
	v_mul_f32_e32 v27, 0x3fb8aa3b, v27
	v_mul_f32_e32 v29, 0x3fb8aa3b, v29
	v_mul_f32_e32 v31, 0x3fb8aa3b, v31
	v_mul_f32_e32 v33, 0x3fb8aa3b, v33
	v_mul_f32_e32 v35, 0x3fb8aa3b, v35
	v_mul_f32_e32 v37, 0x3fb8aa3b, v37
	v_mul_f32_e32 v39, 0x3fb8aa3b, v39
	v_exp_f32_e32 v25, v25
	v_exp_f32_e32 v27, v27
	v_exp_f32_e32 v29, v29
	v_exp_f32_e32 v31, v31
	v_exp_f32_e32 v33, v33
	v_exp_f32_e32 v35, v35
	v_exp_f32_e32 v37, v37
	v_exp_f32_e32 v39, v39
	v_add_f32_e32 v25, 1.0, v25
	v_add_f32_e32 v27, 1.0, v27
	v_add_f32_e32 v29, 1.0, v29
	v_add_f32_e32 v31, 1.0, v31
	v_add_f32_e32 v33, 1.0, v33
	v_add_f32_e32 v35, 1.0, v35
	v_add_f32_e32 v37, 1.0, v37
	v_add_f32_e32 v39, 1.0, v39
	v_rcp_f32_e32 v25, v25
	v_rcp_f32_e32 v27, v27
	v_rcp_f32_e32 v29, v29
	v_rcp_f32_e32 v31, v31
	v_rcp_f32_e32 v33, v33
	v_rcp_f32_e32 v35, v35
	v_rcp_f32_e32 v37, v37
	v_rcp_f32_e32 v39, v39
	v_fma_f32 v25, v25, -2.0, 1.0
	v_fma_f32 v27, v27, -2.0, 1.0
	v_fma_f32 v29, v29, -2.0, 1.0
	v_fma_f32 v31, v31, -2.0, 1.0
	v_fma_f32 v33, v33, -2.0, 1.0
	v_fma_f32 v35, v35, -2.0, 1.0
	v_fma_f32 v37, v37, -2.0, 1.0
	v_fma_f32 v39, v39, -2.0, 1.0
	v_cndmask_b32_e64 v24, v24, v25, s[6:7]
	v_cndmask_b32_e64 v26, v26, v27, s[6:7]
	v_cndmask_b32_e64 v28, v28, v29, s[6:7]
	v_cndmask_b32_e64 v30, v30, v31, s[6:7]
	v_cndmask_b32_e64 v32, v32, v33, s[6:7]
	v_cndmask_b32_e64 v34, v34, v35, s[6:7]
	v_cndmask_b32_e64 v36, v36, v37, s[6:7]
	v_cndmask_b32_e64 v38, v38, v39, s[6:7]
	v_bfe_u32 v25, v24, 16, 1
	v_bfe_u32 v27, v26, 16, 1
	v_bfe_u32 v29, v28, 16, 1
	v_bfe_u32 v31, v30, 16, 1
	v_bfe_u32 v33, v32, 16, 1
	v_bfe_u32 v35, v34, 16, 1
	v_bfe_u32 v37, v36, 16, 1
	v_bfe_u32 v39, v38, 16, 1
	v_add3_u32 v24, v24, v25, s12
	v_add3_u32 v26, v26, v27, s12
	v_add3_u32 v28, v28, v29, s12
	v_add3_u32 v30, v30, v31, s12
	v_add3_u32 v32, v32, v33, s12
	v_add3_u32 v34, v34, v35, s12
	v_add3_u32 v36, v36, v37, s12
	v_add3_u32 v38, v38, v39, s12
	v_add_u32_e32 v25, s21, v140
	v_add_u32_e32 v27, s96, v140
	v_add_u32_e32 v29, s82, v140
	v_add_u32_e32 v31, s22, v140
	v_add_u32_e32 v33, s23, v140
	v_add_u32_e32 v35, s24, v140
	v_add_u32_e32 v37, s83, v140
	v_add_u32_e32 v39, s33, v140
	ds_write_b16_d16_hi v25, v24
	ds_write_b16_d16_hi v27, v26
; DI u16 f2bf(float x) { unsigned u = __float_as_uint(x); u += 0x7fffu + ((u >> 16) & 1u); return (u16)(u >> 16); }
;     ...
;           u16* tdst = ((c < 224) ? twb : tab) + ((c - 192) & 31);
; #pragma unroll
;           for (int j = 0; j < 32; ++j) {
;             const float psv = pv[j + 1] + mu * (0.5f * (pv[j] + pv[j + 2]) - pv[j + 1]);
;             const float th = 1.f - 2.f * __builtin_amdgcn_rcpf(__expf(2.f * psv) + 1.f);
;             tdst[(dir ? 31 - j : j) * 40] = f2bf((c < 224) ? th : psv);
;           }
	ds_write_b16_d16_hi v29, v28
	ds_write_b16_d16_hi v31, v30
	ds_write_b16_d16_hi v33, v32
	ds_write_b16_d16_hi v35, v34
	ds_write_b16_d16_hi v37, v36
	ds_write_b16_d16_hi v39, v38
	v_fma_f32 v24, v123, v75, v48
	v_fma_f32 v26, v123, v74, v45
	v_fma_f32 v28, v123, v73, v14
	v_fma_f32 v30, v123, v72, v11
	v_fma_f32 v32, v123, v71, v8
	v_fma_f32 v34, v123, v70, v6
	v_fma_f32 v36, v123, v69, v3
	v_fma_f32 v38, v123, v68, v15
	v_add_f32_e32 v25, v24, v24
	v_add_f32_e32 v27, v26, v26
	v_add_f32_e32 v29, v28, v28
	v_add_f32_e32 v31, v30, v30
	v_add_f32_e32 v33, v32, v32
	v_add_f32_e32 v35, v34, v34
	v_add_f32_e32 v37, v36, v36
	v_add_f32_e32 v39, v38, v38
	v_mul_f32_e32 v25, 0x3fb8aa3b, v25
	v_mul_f32_e32 v27, 0x3fb8aa3b, v27
	v_mul_f32_e32 v29, 0x3fb8aa3b, v29
	v_mul_f32_e32 v31, 0x3fb8aa3b, v31
	v_mul_f32_e32 v33, 0x3fb8aa3b, v33
	v_mul_f32_e32 v35, 0x3fb8aa3b, v35
	v_mul_f32_e32 v37, 0x3fb8aa3b, v37
	v_mul_f32_e32 v39, 0x3fb8aa3b, v39
	v_exp_f32_e32 v25, v25
	v_exp_f32_e32 v27, v27
	v_exp_f32_e32 v29, v29
	v_exp_f32_e32 v31, v31
	v_exp_f32_e32 v33, v33
	v_exp_f32_e32 v35, v35
	v_exp_f32_e32 v37, v37
	v_exp_f32_e32 v39, v39
	v_add_f32_e32 v25, 1.0, v25
	v_add_f32_e32 v27, 1.0, v27
	v_add_f32_e32 v29, 1.0, v29
	v_add_f32_e32 v31, 1.0, v31
	v_add_f32_e32 v33, 1.0, v33
	v_add_f32_e32 v35, 1.0, v35
	v_add_f32_e32 v37, 1.0, v37
	v_add_f32_e32 v39, 1.0, v39
	v_rcp_f32_e32 v25, v25
	v_rcp_f32_e32 v27, v27
	v_rcp_f32_e32 v29, v29
	v_rcp_f32_e32 v31, v31
	v_rcp_f32_e32 v33, v33
	v_rcp_f32_e32 v35, v35
	v_rcp_f32_e32 v37, v37
	v_rcp_f32_e32 v39, v39
	v_fma_f32 v25, v25, -2.0, 1.0
	v_fma_f32 v27, v27, -2.0, 1.0
	v_fma_f32 v29, v29, -2.0, 1.0
	v_fma_f32 v31, v31, -2.0, 1.0
	v_fma_f32 v33, v33, -2.0, 1.0
	v_fma_f32 v35, v35, -2.0, 1.0
	v_fma_f32 v37, v37, -2.0, 1.0
	v_fma_f32 v39, v39, -2.0, 1.0
	v_cndmask_b32_e64 v24, v24, v25, s[6:7]
	v_cndmask_b32_e64 v26, v26, v27, s[6:7]
	v_cndmask_b32_e64 v28, v28, v29, s[6:7]
	v_cndmask_b32_e64 v30, v30, v31, s[6:7]
	v_cndmask_b32_e64 v32, v32, v33, s[6:7]
	v_cndmask_b32_e64 v34, v34, v35, s[6:7]
	v_cndmask_b32_e64 v36, v36, v37, s[6:7]
	v_cndmask_b32_e64 v38, v38, v39, s[6:7]
	v_bfe_u32 v25, v24, 16, 1
	v_bfe_u32 v27, v26, 16, 1
	v_bfe_u32 v29, v28, 16, 1
	v_bfe_u32 v31, v30, 16, 1
	v_bfe_u32 v33, v32, 16, 1
	v_bfe_u32 v35, v34, 16, 1
	v_bfe_u32 v37, v36, 16, 1
	v_bfe_u32 v39, v38, 16, 1
	v_add3_u32 v24, v24, v25, s12
	v_add3_u32 v26, v26, v27, s12
	v_add3_u32 v28, v28, v29, s12
	v_add3_u32 v30, v30, v31, s12
	v_add3_u32 v32, v32, v33, s12
	v_add3_u32 v34, v34, v35, s12
	v_add3_u32 v36, v36, v37, s12
	v_add3_u32 v38, v38, v39, s12
	v_add_u32_e32 v25, s52, v140
	v_add_u32_e32 v27, s36, v140
	v_add_u32_e32 v29, s37, v140
	v_add_u32_e32 v31, s38, v140
	v_add_u32_e32 v33, s39, v140
	v_add_u32_e32 v35, s40, v140
	v_add_u32_e32 v37, s41, v140
	v_add_u32_e32 v39, s42, v140
	ds_write_b16_d16_hi v25, v24
	ds_write_b16_d16_hi v27, v26
	ds_write_b16_d16_hi v29, v28
	ds_write_b16_d16_hi v31, v30
	ds_write_b16_d16_hi v33, v32
	ds_write_b16_d16_hi v35, v34
	ds_write_b16_d16_hi v37, v36
	ds_write_b16_d16_hi v39, v38
	v_fma_f32 v24, v123, v67, v12
	v_fma_f32 v26, v123, v66, v9
	v_fma_f32 v28, v123, v65, v7
	v_fma_f32 v30, v123, v64, v4
	v_fma_f32 v32, v123, v63, v5
	v_fma_f32 v34, v123, v62, v2
	v_fma_f32 v36, v123, v61, v1
	v_fma_f32 v38, v123, v60, v0
	v_add_f32_e32 v25, v24, v24
	v_add_f32_e32 v27, v26, v26
	v_add_f32_e32 v29, v28, v28
	v_add_f32_e32 v31, v30, v30
	v_add_f32_e32 v33, v32, v32
	v_add_f32_e32 v35, v34, v34
	v_add_f32_e32 v37, v36, v36
	v_add_f32_e32 v39, v38, v38
	v_mul_f32_e32 v25, 0x3fb8aa3b, v25
	v_mul_f32_e32 v27, 0x3fb8aa3b, v27
	v_mul_f32_e32 v29, 0x3fb8aa3b, v29
	v_mul_f32_e32 v31, 0x3fb8aa3b, v31
	v_mul_f32_e32 v33, 0x3fb8aa3b, v33
	v_mul_f32_e32 v35, 0x3fb8aa3b, v35
	v_mul_f32_e32 v37, 0x3fb8aa3b, v37
	v_mul_f32_e32 v39, 0x3fb8aa3b, v39
	v_exp_f32_e32 v25, v25
	v_exp_f32_e32 v27, v27
	v_exp_f32_e32 v29, v29
	v_exp_f32_e32 v31, v31
	v_exp_f32_e32 v33, v33
	v_exp_f32_e32 v35, v35
	v_exp_f32_e32 v37, v37
	v_exp_f32_e32 v39, v39
	v_add_f32_e32 v25, 1.0, v25
	v_add_f32_e32 v27, 1.0, v27
	v_add_f32_e32 v29, 1.0, v29
	v_add_f32_e32 v31, 1.0, v31
	v_add_f32_e32 v33, 1.0, v33
	v_add_f32_e32 v35, 1.0, v35
	v_add_f32_e32 v37, 1.0, v37
	v_add_f32_e32 v39, 1.0, v39
	v_rcp_f32_e32 v25, v25
	v_rcp_f32_e32 v27, v27
	v_rcp_f32_e32 v29, v29
	v_rcp_f32_e32 v31, v31
	v_rcp_f32_e32 v33, v33
	v_rcp_f32_e32 v35, v35
	v_rcp_f32_e32 v37, v37
	v_rcp_f32_e32 v39, v39
	v_fma_f32 v25, v25, -2.0, 1.0
	v_fma_f32 v27, v27, -2.0, 1.0
	v_fma_f32 v29, v29, -2.0, 1.0
	v_fma_f32 v31, v31, -2.0, 1.0
	v_fma_f32 v33, v33, -2.0, 1.0
	v_fma_f32 v35, v35, -2.0, 1.0
	v_fma_f32 v37, v37, -2.0, 1.0
	v_fma_f32 v39, v39, -2.0, 1.0
	v_cndmask_b32_e64 v24, v24, v25, s[6:7]
	v_cndmask_b32_e64 v26, v26, v27, s[6:7]
	v_cndmask_b32_e64 v28, v28, v29, s[6:7]
	v_cndmask_b32_e64 v30, v30, v31, s[6:7]
	v_cndmask_b32_e64 v32, v32, v33, s[6:7]
	v_cndmask_b32_e64 v34, v34, v35, s[6:7]
	v_cndmask_b32_e64 v36, v36, v37, s[6:7]
	v_cndmask_b32_e64 v38, v38, v39, s[6:7]
	v_bfe_u32 v25, v24, 16, 1
	v_bfe_u32 v27, v26, 16, 1
	v_bfe_u32 v29, v28, 16, 1
	v_bfe_u32 v31, v30, 16, 1
	v_bfe_u32 v33, v32, 16, 1
	v_bfe_u32 v35, v34, 16, 1
	v_bfe_u32 v37, v36, 16, 1
	v_bfe_u32 v39, v38, 16, 1
	v_add3_u32 v24, v24, v25, s12
	v_add3_u32 v26, v26, v27, s12
	v_add3_u32 v28, v28, v29, s12
	v_add3_u32 v30, v30, v31, s12
	v_add3_u32 v32, v32, v33, s12
	v_add3_u32 v34, v34, v35, s12
	v_add3_u32 v36, v36, v37, s12
	v_add3_u32 v38, v38, v39, s12
	v_add_u32_e32 v25, s43, v140
	v_add_u32_e32 v27, s44, v140
	v_add_u32_e32 v29, s45, v140
	v_add_u32_e32 v31, s46, v140
	v_add_u32_e32 v33, s47, v140
	v_add_u32_e32 v35, s48, v140
	v_add_u32_e32 v37, s49, v140
	v_add_u32_e32 v39, s50, v140
	ds_write_b16_d16_hi v25, v24
	ds_write_b16_d16_hi v27, v26
	ds_write_b16_d16_hi v29, v28
	ds_write_b16_d16_hi v31, v30
	ds_write_b16_d16_hi v33, v32
	ds_write_b16_d16_hi v35, v34
	ds_write_b16_d16_hi v37, v36
	ds_write_b16_d16_hi v39, v38
	s_mov_b64 s[12:13], 0

; #define MFMA32(a, b, c) __builtin_amdgcn_mfma_f32_32x32x16_bf16((a), (b), (c), 0, 0, 0)
; DI int crow(int i, int h) { return (i & 3) + 8 * (i >> 2) + 4 * h; }
;     ...
;       if (!(pm & 4)) {
;         const int r = lane & 31, hq = lane >> 5;
;         const u16* asrc = ((wv >> 1) ? tab : twb) + r * 40 + 8 * hq;
;         const bf16x8 af0 = *(const bf16x8*)(asrc), af1 = *(const bf16x8*)(asrc + 16);
;         f32x16 accl;
; #pragma unroll
;         for (int i = 0; i < 16; ++i) accl[i] = 0.f;
;         accl = MFMA32(af0, bfr0, accl);
;         accl = MFMA32(af1, bfr1, accl);
;         float* odst = prep + ((wv >> 1) ? 128 : 64) + (wv & 1) * 32 + r;
; #pragma unroll
;         for (int i = 0; i < 16; ++i) odst[crow(i, hq) * 384] = accl[i];
;       }
;       __syncthreads();
;       if (!(pm & 4)) {
;         const int n0 = nx * 32;
; #pragma unroll 2
;         for (int s = 0; s < 8; ++s) {
;           const int step = tg * 8 + s;
;           float* pp = prep + step * 384;
;           const float wacc = w0 + pp[64 + kB], aacc = a0 + pp[128 + kB];
;           const float sg = __builtin_amdgcn_rcpf(1.f + __expf(-wacc));
;           const float decay = __expf(-0.6065306597126334f * sg);
;           const float av = __builtin_amdgcn_rcpf(1.f + __expf(-aacc));
;           const float ksv = pp[192 + kB];
;           const float xk = ksv * kkwB;
;           const float kk = xk * rsqrtf(fmaxf(wave_sum(xk * xk), 1e-24f));
;           const float kd = ksv * (1.f + (av - 1.f) * ka);
;           pp[64 + kB] = decay; pp[192 + kB] = kd; pp[128 + kB] = kk * av; pp[kB] = -kk;
.LBB0_380:
	s_waitcnt lgkmcnt(0)
	s_barrier
	ds_read_b128 v[0:3], v149
	ds_read_b128 v[46:49], v149 offset:32
	s_mov_b32 s76, 8
	v_mov_b32_e32 v44, v148
	s_waitcnt lgkmcnt(1)
	v_mfma_f32_32x32x16_bf16 v[0:15], v[0:3], v[16:19], 0
	s_waitcnt lgkmcnt(0)
	v_mfma_f32_32x32x16_bf16 v[0:15], v[46:49], v[20:23], v[0:15]
	s_nop 11
	ds_write2st64_b32 v150, v0, v1 offset1:6
	ds_write2st64_b32 v150, v2, v3 offset0:12 offset1:18
	ds_write2st64_b32 v150, v4, v5 offset0:48 offset1:54
	ds_write2st64_b32 v150, v6, v7 offset0:60 offset1:66
	ds_write2st64_b32 v150, v8, v9 offset0:96 offset1:102
	ds_write2st64_b32 v150, v10, v11 offset0:108 offset1:114
	ds_write2st64_b32 v150, v12, v13 offset0:144 offset1:150
	ds_write2st64_b32 v150, v14, v15 offset0:156 offset1:162
	v_mov_b32_e32 v0, v130
	s_waitcnt lgkmcnt(0)
	s_barrier
	ds_read2st64_b32 v[46:47], v148 offset0:1 offset1:2
	ds_read2st64_b32 v[56:57], v148 offset0:7 offset1:8
	ds_read2st64_b32 v[66:67], v148 offset0:13 offset1:14
	ds_read2st64_b32 v[76:77], v148 offset0:19 offset1:20
	ds_read2st64_b32 v[86:87], v148 offset0:25 offset1:26
	ds_read2st64_b32 v[24:25], v148 offset0:31 offset1:32
	ds_read2st64_b32 v[34:35], v148 offset0:37 offset1:38
	ds_read2st64_b32 v[2:3], v148 offset0:43 offset1:44
	s_waitcnt lgkmcnt(0)
	ds_read2st64_b32 v[48:49], v148 offset0:3 offset1:4
	ds_read2st64_b32 v[58:59], v148 offset0:9 offset1:10
	ds_read2st64_b32 v[68:69], v148 offset0:15 offset1:16
	ds_read2st64_b32 v[78:79], v148 offset0:21 offset1:22
	ds_read2st64_b32 v[88:89], v148 offset0:27 offset1:28
	ds_read2st64_b32 v[26:27], v148 offset0:33 offset1:34
	ds_read2st64_b32 v[36:37], v148 offset0:39 offset1:40
	ds_read2st64_b32 v[4:5], v148 offset0:45 offset1:46
	v_add_f32_e32 v50, v124, v46
	v_add_f32_e32 v60, v124, v56
	v_add_f32_e32 v70, v124, v66
	v_add_f32_e32 v80, v124, v76
	v_add_f32_e32 v90, v124, v86
	v_add_f32_e32 v28, v124, v24
	v_add_f32_e32 v38, v124, v34
	v_add_f32_e32 v6, v124, v2
	v_add_f32_e32 v46, v125, v47
	v_add_f32_e32 v56, v125, v57
	v_add_f32_e32 v66, v125, v67
	v_add_f32_e32 v76, v125, v77
	v_add_f32_e32 v86, v125, v87
	v_add_f32_e32 v24, v125, v25
	v_add_f32_e32 v34, v125, v35
	v_add_f32_e32 v2, v125, v3
	v_mul_f32_e32 v46, 0xbfb8aa3b, v46
	v_mul_f32_e32 v56, 0xbfb8aa3b, v56
	v_mul_f32_e32 v66, 0xbfb8aa3b, v66
	v_mul_f32_e32 v76, 0xbfb8aa3b, v76
	v_mul_f32_e32 v86, 0xbfb8aa3b, v86
	v_mul_f32_e32 v24, 0xbfb8aa3b, v24
	v_mul_f32_e32 v34, 0xbfb8aa3b, v34
	v_mul_f32_e32 v2, 0xbfb8aa3b, v2
	v_exp_f32_e32 v46, v46
	v_exp_f32_e32 v56, v56
	v_exp_f32_e32 v66, v66
	v_exp_f32_e32 v76, v76
	v_exp_f32_e32 v86, v86
	v_exp_f32_e32 v24, v24
	v_exp_f32_e32 v34, v34
	v_exp_f32_e32 v2, v2
	v_mul_f32_e32 v50, 0xbfb8aa3b, v50
	v_mul_f32_e32 v60, 0xbfb8aa3b, v60
	v_mul_f32_e32 v70, 0xbfb8aa3b, v70
	v_mul_f32_e32 v80, 0xbfb8aa3b, v80
	v_mul_f32_e32 v90, 0xbfb8aa3b, v90
	v_mul_f32_e32 v28, 0xbfb8aa3b, v28
	v_mul_f32_e32 v38, 0xbfb8aa3b, v38
	v_mul_f32_e32 v6, 0xbfb8aa3b, v6
	v_exp_f32_e32 v50, v50
	v_exp_f32_e32 v60, v60
	v_exp_f32_e32 v70, v70
	v_exp_f32_e32 v80, v80
	v_exp_f32_e32 v90, v90
	v_exp_f32_e32 v28, v28
	v_exp_f32_e32 v38, v38
	v_exp_f32_e32 v6, v6
	v_add_f32_e32 v46, 1.0, v46
	v_add_f32_e32 v56, 1.0, v56
	v_add_f32_e32 v66, 1.0, v66
	v_add_f32_e32 v76, 1.0, v76
	v_add_f32_e32 v86, 1.0, v86
	v_add_f32_e32 v24, 1.0, v24
	v_add_f32_e32 v34, 1.0, v34
	v_add_f32_e32 v2, 1.0, v2
	v_rcp_f32_e32 v51, v46
	v_rcp_f32_e32 v61, v56
	v_rcp_f32_e32 v71, v66
	v_rcp_f32_e32 v81, v76
	v_rcp_f32_e32 v91, v86
	v_rcp_f32_e32 v29, v24
	v_rcp_f32_e32 v39, v34
	v_rcp_f32_e32 v7, v2
	v_add_f32_e32 v50, 1.0, v50
	v_add_f32_e32 v60, 1.0, v60
	v_add_f32_e32 v70, 1.0, v70
	v_add_f32_e32 v80, 1.0, v80
	v_add_f32_e32 v90, 1.0, v90
	v_add_f32_e32 v28, 1.0, v28
	v_add_f32_e32 v38, 1.0, v38
	v_add_f32_e32 v6, 1.0, v6
	v_rcp_f32_e32 v50, v50
	v_rcp_f32_e32 v60, v60
	v_rcp_f32_e32 v70, v70
	v_rcp_f32_e32 v80, v80
	v_rcp_f32_e32 v90, v90
	v_rcp_f32_e32 v28, v28
	v_rcp_f32_e32 v38, v38
	v_rcp_f32_e32 v6, v6
	s_waitcnt lgkmcnt(0)
	v_mul_f32_e32 v52, v128, v48
	v_mul_f32_e32 v62, v128, v58
	v_mul_f32_e32 v72, v128, v68
	v_mul_f32_e32 v82, v128, v78
	v_mul_f32_e32 v92, v128, v88
	v_mul_f32_e32 v30, v128, v26
	v_mul_f32_e32 v40, v128, v36
	v_mul_f32_e32 v8, v128, v4
	v_mul_f32_e32 v53, v52, v52
	v_mul_f32_e32 v63, v62, v62
	v_mul_f32_e32 v73, v72, v72
	v_mul_f32_e32 v83, v82, v82
	v_mul_f32_e32 v93, v92, v92
	v_mul_f32_e32 v31, v30, v30
	v_mul_f32_e32 v41, v40, v40
	v_mul_f32_e32 v9, v8, v8
	v_mul_f32_e32 v50, 0xbf1b4598, v50
	v_mul_f32_e32 v60, 0xbf1b4598, v60
	v_mul_f32_e32 v70, 0xbf1b4598, v70
	v_mul_f32_e32 v80, 0xbf1b4598, v80
	v_mul_f32_e32 v90, 0xbf1b4598, v90
	v_mul_f32_e32 v28, 0xbf1b4598, v28
	v_mul_f32_e32 v38, 0xbf1b4598, v38
	v_mul_f32_e32 v6, 0xbf1b4598, v6
	v_mul_f32_e32 v50, 0x3fb8aa3b, v50
	v_mul_f32_e32 v60, 0x3fb8aa3b, v60
	v_mul_f32_e32 v70, 0x3fb8aa3b, v70
	v_mul_f32_e32 v80, 0x3fb8aa3b, v80
	v_mul_f32_e32 v90, 0x3fb8aa3b, v90
	v_mul_f32_e32 v28, 0x3fb8aa3b, v28
	v_mul_f32_e32 v38, 0x3fb8aa3b, v38
	v_mul_f32_e32 v6, 0x3fb8aa3b, v6
	v_mov_b32_dpp v53, v53 quad_perm:[1,0,3,2] row_mask:0xf bank_mask:0xf bound_ctrl:1
	v_mov_b32_dpp v63, v63 quad_perm:[1,0,3,2] row_mask:0xf bank_mask:0xf bound_ctrl:1
	v_mov_b32_dpp v73, v73 quad_perm:[1,0,3,2] row_mask:0xf bank_mask:0xf bound_ctrl:1
	v_mov_b32_dpp v83, v83 quad_perm:[1,0,3,2] row_mask:0xf bank_mask:0xf bound_ctrl:1
	v_mov_b32_dpp v93, v93 quad_perm:[1,0,3,2] row_mask:0xf bank_mask:0xf bound_ctrl:1
	v_mov_b32_dpp v31, v31 quad_perm:[1,0,3,2] row_mask:0xf bank_mask:0xf bound_ctrl:1
	v_mov_b32_dpp v41, v41 quad_perm:[1,0,3,2] row_mask:0xf bank_mask:0xf bound_ctrl:1
; DI float wave_sum(float x) {
;   x += dpp_f(x, 0); x += dpp_f(x, 1); x += dpp_f(x, 2);
;   x += __int_as_float(__builtin_amdgcn_update_dpp(0, __float_as_int(x), 0x140, 0xF, 0xF, true));
;   const int xi = __float_as_int(x);
;   const float a = __int_as_float(__builtin_amdgcn_readlane(xi, 0)), b = __int_as_float(__builtin_amdgcn_readlane(xi, 16));
;   const float c = __int_as_float(__builtin_amdgcn_readlane(xi, 32)), d = __int_as_float(__builtin_amdgcn_readlane(xi, 48));
;   return (a + b) + (c + d);
;     ...
;           float* pp = prep + step * 384;
;           const float wacc = w0 + pp[64 + kB], aacc = a0 + pp[128 + kB];
;           const float sg = __builtin_amdgcn_rcpf(1.f + __expf(-wacc));
;           const float decay = __expf(-0.6065306597126334f * sg);
;           const float av = __builtin_amdgcn_rcpf(1.f + __expf(-aacc));
;           const float ksv = pp[192 + kB];
;           const float xk = ksv * kkwB;
;           const float kk = xk * rsqrtf(fmaxf(wave_sum(xk * xk), 1e-24f));
;           const float kd = ksv * (1.f + (av - 1.f) * ka);
;           pp[64 + kB] = decay; pp[192 + kB] = kd; pp[128 + kB] = kk * av; pp[kB] = -kk;
	v_mov_b32_dpp v9, v9 quad_perm:[1,0,3,2] row_mask:0xf bank_mask:0xf bound_ctrl:1
	v_fmac_f32_e32 v53, v52, v52
	v_fmac_f32_e32 v63, v62, v62
	v_fmac_f32_e32 v73, v72, v72
	v_fmac_f32_e32 v83, v82, v82
	v_fmac_f32_e32 v93, v92, v92
	v_fmac_f32_e32 v31, v30, v30
	v_fmac_f32_e32 v41, v40, v40
	v_fmac_f32_e32 v9, v8, v8
	v_exp_f32_e32 v50, v50
	v_exp_f32_e32 v60, v60
	v_exp_f32_e32 v70, v70
	v_exp_f32_e32 v80, v80
	v_exp_f32_e32 v90, v90
	v_exp_f32_e32 v28, v28
	v_exp_f32_e32 v38, v38
	v_exp_f32_e32 v6, v6
	v_add_f32_dpp v53, v53, v53 quad_perm:[2,3,0,1] row_mask:0xf bank_mask:0xf bound_ctrl:1
	v_add_f32_dpp v63, v63, v63 quad_perm:[2,3,0,1] row_mask:0xf bank_mask:0xf bound_ctrl:1
	v_add_f32_dpp v73, v73, v73 quad_perm:[2,3,0,1] row_mask:0xf bank_mask:0xf bound_ctrl:1
	v_add_f32_dpp v83, v83, v83 quad_perm:[2,3,0,1] row_mask:0xf bank_mask:0xf bound_ctrl:1
	v_add_f32_dpp v93, v93, v93 quad_perm:[2,3,0,1] row_mask:0xf bank_mask:0xf bound_ctrl:1
	v_add_f32_dpp v31, v31, v31 quad_perm:[2,3,0,1] row_mask:0xf bank_mask:0xf bound_ctrl:1
	v_add_f32_dpp v41, v41, v41 quad_perm:[2,3,0,1] row_mask:0xf bank_mask:0xf bound_ctrl:1
	v_add_f32_dpp v9, v9, v9 quad_perm:[2,3,0,1] row_mask:0xf bank_mask:0xf bound_ctrl:1
	v_add_f32_dpp v53, v53, v53 row_half_mirror row_mask:0xf bank_mask:0xf bound_ctrl:1
	v_add_f32_dpp v63, v63, v63 row_half_mirror row_mask:0xf bank_mask:0xf bound_ctrl:1
	v_add_f32_dpp v73, v73, v73 row_half_mirror row_mask:0xf bank_mask:0xf bound_ctrl:1
	v_add_f32_dpp v83, v83, v83 row_half_mirror row_mask:0xf bank_mask:0xf bound_ctrl:1
	v_add_f32_dpp v93, v93, v93 row_half_mirror row_mask:0xf bank_mask:0xf bound_ctrl:1
	v_add_f32_dpp v31, v31, v31 row_half_mirror row_mask:0xf bank_mask:0xf bound_ctrl:1
	v_add_f32_dpp v41, v41, v41 row_half_mirror row_mask:0xf bank_mask:0xf bound_ctrl:1
	v_add_f32_dpp v9, v9, v9 row_half_mirror row_mask:0xf bank_mask:0xf bound_ctrl:1
	v_add_f32_dpp v53, v53, v53 row_mirror row_mask:0xf bank_mask:0xf bound_ctrl:1
	v_add_f32_dpp v63, v63, v63 row_mirror row_mask:0xf bank_mask:0xf bound_ctrl:1
	v_add_f32_dpp v73, v73, v73 row_mirror row_mask:0xf bank_mask:0xf bound_ctrl:1
	v_add_f32_dpp v83, v83, v83 row_mirror row_mask:0xf bank_mask:0xf bound_ctrl:1
	v_add_f32_dpp v93, v93, v93 row_mirror row_mask:0xf bank_mask:0xf bound_ctrl:1
	v_add_f32_dpp v31, v31, v31 row_mirror row_mask:0xf bank_mask:0xf bound_ctrl:1
	v_add_f32_dpp v41, v41, v41 row_mirror row_mask:0xf bank_mask:0xf bound_ctrl:1
	v_add_f32_dpp v9, v9, v9 row_mirror row_mask:0xf bank_mask:0xf bound_ctrl:1
	v_mov_b32_e32 v55, v53
	v_mov_b32_e32 v65, v63
	v_mov_b32_e32 v75, v73
	v_mov_b32_e32 v85, v83
	v_mov_b32_e32 v95, v93
	v_mov_b32_e32 v33, v31
	v_mov_b32_e32 v43, v41
	v_mov_b32_e32 v11, v9
	v_permlane16_swap_b32_e32 v53, v55
	v_permlane16_swap_b32_e32 v63, v65
	v_permlane16_swap_b32_e32 v73, v75
	v_permlane16_swap_b32_e32 v83, v85
	v_permlane16_swap_b32_e32 v93, v95
	v_permlane16_swap_b32_e32 v31, v33
	v_permlane16_swap_b32_e32 v41, v43
	v_permlane16_swap_b32_e32 v9, v11
	v_add_f32_e32 v53, v53, v55
	v_add_f32_e32 v63, v63, v65
	v_add_f32_e32 v73, v73, v75
	v_add_f32_e32 v83, v83, v85
	v_add_f32_e32 v93, v93, v95
	v_add_f32_e32 v31, v31, v33
	v_add_f32_e32 v41, v41, v43
	v_add_f32_e32 v9, v9, v11
	v_mov_b32_e32 v55, v53
	v_mov_b32_e32 v65, v63
	v_mov_b32_e32 v75, v73
	v_mov_b32_e32 v85, v83
	v_mov_b32_e32 v95, v93
	v_mov_b32_e32 v33, v31
	v_mov_b32_e32 v43, v41
	v_mov_b32_e32 v11, v9
	v_permlane32_swap_b32_e32 v53, v55
	v_permlane32_swap_b32_e32 v63, v65
	v_permlane32_swap_b32_e32 v73, v75
	v_permlane32_swap_b32_e32 v83, v85
	v_permlane32_swap_b32_e32 v93, v95
	v_permlane32_swap_b32_e32 v31, v33
	v_permlane32_swap_b32_e32 v41, v43
	v_permlane32_swap_b32_e32 v9, v11
	v_add_f32_e32 v53, v53, v55
	v_add_f32_e32 v63, v63, v65
	v_add_f32_e32 v73, v73, v75
	v_add_f32_e32 v83, v83, v85
	v_add_f32_e32 v93, v93, v95
	v_add_f32_e32 v31, v31, v33
	v_add_f32_e32 v41, v41, v43
	v_add_f32_e32 v9, v9, v11
	v_max_f32_e32 v53, 0x179abe15, v53
	v_max_f32_e32 v63, 0x179abe15, v63
	v_max_f32_e32 v73, 0x179abe15, v73
	v_max_f32_e32 v83, 0x179abe15, v83
	v_max_f32_e32 v93, 0x179abe15, v93
	v_max_f32_e32 v31, 0x179abe15, v31
	v_max_f32_e32 v41, 0x179abe15, v41
	v_max_f32_e32 v9, 0x179abe15, v9
	v_rsq_f32_e32 v53, v53
	v_rsq_f32_e32 v63, v63
	v_rsq_f32_e32 v73, v73
	v_rsq_f32_e32 v83, v83
	v_rsq_f32_e32 v93, v93
	v_rsq_f32_e32 v31, v31
	v_rsq_f32_e32 v41, v41
	v_rsq_f32_e32 v9, v9
	v_add_f32_e32 v54, -1.0, v51
	v_add_f32_e32 v64, -1.0, v61
	v_add_f32_e32 v74, -1.0, v71
	v_add_f32_e32 v84, -1.0, v81
	v_add_f32_e32 v94, -1.0, v91
	v_add_f32_e32 v32, -1.0, v29
	v_add_f32_e32 v42, -1.0, v39
	v_add_f32_e32 v10, -1.0, v7
	v_fma_f32 v54, v126, v54, 1.0
	v_fma_f32 v64, v126, v64, 1.0
	v_fma_f32 v74, v126, v74, 1.0
	v_fma_f32 v84, v126, v84, 1.0
	v_fma_f32 v94, v126, v94, 1.0
	v_fma_f32 v32, v126, v32, 1.0
	v_fma_f32 v42, v126, v42, 1.0
	v_fma_f32 v10, v126, v10, 1.0
	v_mul_f32_e32 v48, v48, v54
	v_mul_f32_e32 v58, v58, v64
	v_mul_f32_e32 v68, v68, v74
	v_mul_f32_e32 v78, v78, v84
	v_mul_f32_e32 v88, v88, v94
	v_mul_f32_e32 v26, v26, v32
	v_mul_f32_e32 v36, v36, v42
	v_mul_f32_e32 v4, v4, v10
	v_mul_f32_e64 v52, v52, -v53
	v_mul_f32_e64 v62, v62, -v63
	v_mul_f32_e64 v72, v72, -v73
	v_mul_f32_e64 v82, v82, -v83
	v_mul_f32_e64 v92, v92, -v93
	v_mul_f32_e64 v30, v30, -v31
	v_mul_f32_e64 v40, v40, -v41
	v_mul_f32_e64 v8, v8, -v9
	v_mul_f32_e64 v51, v51, -v52
	v_mul_f32_e64 v61, v61, -v62
	v_mul_f32_e64 v71, v71, -v72
	v_mul_f32_e64 v81, v81, -v82
	v_mul_f32_e64 v91, v91, -v92
	v_mul_f32_e64 v29, v29, -v30
	v_mul_f32_e64 v39, v39, -v40
	v_mul_f32_e64 v7, v7, -v8
; DI float wave_sum(float x) {
;   x += dpp_f(x, 0); x += dpp_f(x, 1); x += dpp_f(x, 2);
;   x += __int_as_float(__builtin_amdgcn_update_dpp(0, __float_as_int(x), 0x140, 0xF, 0xF, true));
;   const int xi = __float_as_int(x);
;   const float a = __int_as_float(__builtin_amdgcn_readlane(xi, 0)), b = __int_as_float(__builtin_amdgcn_readlane(xi, 16));
;   const float c = __int_as_float(__builtin_amdgcn_readlane(xi, 32)), d = __int_as_float(__builtin_amdgcn_readlane(xi, 48));
;   return (a + b) + (c + d);
;     ...
;           pp[64 + kB] = decay; pp[192 + kB] = kd; pp[128 + kB] = kk * av; pp[kB] = -kk;
;           const float cs = wave_sum(pp[256 + kB] * kd * rk);
;           if (lane == 0 && hf == 0 && !(pm & 8)) {
;             const int n = n0 + step;
;             const int tok = dir ? (n < 256 ? 255 - n : 2559 - n) : n;
;             P.cbuf[((size_t)(dir * MALL + b * TALL + tok)) * 4 + hh] = cs;
	ds_write2st64_b32 v148, v51, v48 offset0:2 offset1:3
	ds_write2st64_b32 v148, v61, v58 offset0:8 offset1:9
	ds_write2st64_b32 v148, v71, v68 offset0:14 offset1:15
	ds_write2st64_b32 v148, v81, v78 offset0:20 offset1:21
	ds_write2st64_b32 v148, v91, v88 offset0:26 offset1:27
	ds_write2st64_b32 v148, v29, v26 offset0:32 offset1:33
	ds_write2st64_b32 v148, v39, v36 offset0:38 offset1:39
	ds_write2st64_b32 v148, v7, v4 offset0:44 offset1:45
	ds_write2st64_b32 v148, v52, v50 offset1:1
	ds_write2st64_b32 v148, v62, v60 offset0:6 offset1:7
	ds_write2st64_b32 v148, v72, v70 offset0:12 offset1:13
	ds_write2st64_b32 v148, v82, v80 offset0:18 offset1:19
	ds_write2st64_b32 v148, v92, v90 offset0:24 offset1:25
	ds_write2st64_b32 v148, v30, v28 offset0:30 offset1:31
	ds_write2st64_b32 v148, v40, v38 offset0:36 offset1:37
	ds_write2st64_b32 v148, v8, v6 offset0:42 offset1:43
	v_mul_f32_e32 v50, v48, v49
	v_mul_f32_e32 v60, v58, v59
	v_mul_f32_e32 v70, v68, v69
	v_mul_f32_e32 v80, v78, v79
	v_mul_f32_e32 v90, v88, v89
	v_mul_f32_e32 v28, v26, v27
	v_mul_f32_e32 v38, v36, v37
	v_mul_f32_e32 v6, v4, v5
	v_mul_f32_e32 v46, v127, v50
	v_mul_f32_e32 v56, v127, v60
	v_mul_f32_e32 v66, v127, v70
	v_mul_f32_e32 v76, v127, v80
	v_mul_f32_e32 v86, v127, v90
	v_mul_f32_e32 v24, v127, v28
	v_mul_f32_e32 v34, v127, v38
	v_mul_f32_e32 v2, v127, v6
	v_mov_b32_dpp v46, v46 quad_perm:[1,0,3,2] row_mask:0xf bank_mask:0xf bound_ctrl:1
	v_mov_b32_dpp v56, v56 quad_perm:[1,0,3,2] row_mask:0xf bank_mask:0xf bound_ctrl:1
	v_mov_b32_dpp v66, v66 quad_perm:[1,0,3,2] row_mask:0xf bank_mask:0xf bound_ctrl:1
	v_mov_b32_dpp v76, v76 quad_perm:[1,0,3,2] row_mask:0xf bank_mask:0xf bound_ctrl:1
	v_mov_b32_dpp v86, v86 quad_perm:[1,0,3,2] row_mask:0xf bank_mask:0xf bound_ctrl:1
	v_mov_b32_dpp v24, v24 quad_perm:[1,0,3,2] row_mask:0xf bank_mask:0xf bound_ctrl:1
	v_mov_b32_dpp v34, v34 quad_perm:[1,0,3,2] row_mask:0xf bank_mask:0xf bound_ctrl:1
	v_mov_b32_dpp v2, v2 quad_perm:[1,0,3,2] row_mask:0xf bank_mask:0xf bound_ctrl:1
	v_fmac_f32_e32 v46, v127, v50
	v_fmac_f32_e32 v56, v127, v60
	v_fmac_f32_e32 v66, v127, v70
	v_fmac_f32_e32 v76, v127, v80
	v_fmac_f32_e32 v86, v127, v90
	v_fmac_f32_e32 v24, v127, v28
	v_fmac_f32_e32 v34, v127, v38
	v_fmac_f32_e32 v2, v127, v6
	v_add_f32_dpp v50, v46, v46 quad_perm:[2,3,0,1] row_mask:0xf bank_mask:0xf bound_ctrl:1
	v_add_f32_dpp v60, v56, v56 quad_perm:[2,3,0,1] row_mask:0xf bank_mask:0xf bound_ctrl:1
	v_add_f32_dpp v70, v66, v66 quad_perm:[2,3,0,1] row_mask:0xf bank_mask:0xf bound_ctrl:1
	v_add_f32_dpp v80, v76, v76 quad_perm:[2,3,0,1] row_mask:0xf bank_mask:0xf bound_ctrl:1
	v_add_f32_dpp v90, v86, v86 quad_perm:[2,3,0,1] row_mask:0xf bank_mask:0xf bound_ctrl:1
	v_add_f32_dpp v28, v24, v24 quad_perm:[2,3,0,1] row_mask:0xf bank_mask:0xf bound_ctrl:1
	v_add_f32_dpp v38, v34, v34 quad_perm:[2,3,0,1] row_mask:0xf bank_mask:0xf bound_ctrl:1
	v_add_f32_dpp v6, v2, v2 quad_perm:[2,3,0,1] row_mask:0xf bank_mask:0xf bound_ctrl:1
	v_add_f32_dpp v50, v50, v50 row_half_mirror row_mask:0xf bank_mask:0xf bound_ctrl:1
	v_add_f32_dpp v60, v60, v60 row_half_mirror row_mask:0xf bank_mask:0xf bound_ctrl:1
	v_add_f32_dpp v70, v70, v70 row_half_mirror row_mask:0xf bank_mask:0xf bound_ctrl:1
	v_add_f32_dpp v80, v80, v80 row_half_mirror row_mask:0xf bank_mask:0xf bound_ctrl:1
	v_add_f32_dpp v90, v90, v90 row_half_mirror row_mask:0xf bank_mask:0xf bound_ctrl:1
	v_add_f32_dpp v28, v28, v28 row_half_mirror row_mask:0xf bank_mask:0xf bound_ctrl:1
	v_add_f32_dpp v38, v38, v38 row_half_mirror row_mask:0xf bank_mask:0xf bound_ctrl:1
	v_add_f32_dpp v6, v6, v6 row_half_mirror row_mask:0xf bank_mask:0xf bound_ctrl:1
	v_add_f32_dpp v50, v50, v50 row_mirror row_mask:0xf bank_mask:0xf bound_ctrl:1
	v_add_f32_dpp v60, v60, v60 row_mirror row_mask:0xf bank_mask:0xf bound_ctrl:1
	v_add_f32_dpp v70, v70, v70 row_mirror row_mask:0xf bank_mask:0xf bound_ctrl:1
	v_add_f32_dpp v80, v80, v80 row_mirror row_mask:0xf bank_mask:0xf bound_ctrl:1
	v_add_f32_dpp v90, v90, v90 row_mirror row_mask:0xf bank_mask:0xf bound_ctrl:1
	v_add_f32_dpp v28, v28, v28 row_mirror row_mask:0xf bank_mask:0xf bound_ctrl:1
	v_add_f32_dpp v38, v38, v38 row_mirror row_mask:0xf bank_mask:0xf bound_ctrl:1
	v_add_f32_dpp v6, v6, v6 row_mirror row_mask:0xf bank_mask:0xf bound_ctrl:1
	v_mov_b32_e32 v55, v50
	v_mov_b32_e32 v65, v60
	v_mov_b32_e32 v75, v70
	v_mov_b32_e32 v85, v80
	v_mov_b32_e32 v95, v90
	v_mov_b32_e32 v33, v28
	v_mov_b32_e32 v43, v38
	v_mov_b32_e32 v11, v6
	v_permlane16_swap_b32_e32 v50, v55
	v_permlane16_swap_b32_e32 v60, v65
	v_permlane16_swap_b32_e32 v70, v75
	v_permlane16_swap_b32_e32 v80, v85
	v_permlane16_swap_b32_e32 v90, v95
	v_permlane16_swap_b32_e32 v28, v33
	v_permlane16_swap_b32_e32 v38, v43
	v_permlane16_swap_b32_e32 v6, v11
	v_add_f32_e32 v50, v50, v55
	v_add_f32_e32 v60, v60, v65
	v_add_f32_e32 v70, v70, v75
	v_add_f32_e32 v80, v80, v85
	v_add_f32_e32 v90, v90, v95
	v_add_f32_e32 v28, v28, v33
	v_add_f32_e32 v38, v38, v43
	v_add_f32_e32 v6, v6, v11
	v_mov_b32_e32 v55, v50
	v_mov_b32_e32 v65, v60
	v_mov_b32_e32 v75, v70
	v_mov_b32_e32 v85, v80
	v_mov_b32_e32 v95, v90
	v_mov_b32_e32 v33, v28
	v_mov_b32_e32 v43, v38
	v_mov_b32_e32 v11, v6
	v_permlane32_swap_b32_e32 v50, v55
	v_permlane32_swap_b32_e32 v60, v65
	v_permlane32_swap_b32_e32 v70, v75
	v_permlane32_swap_b32_e32 v80, v85
	v_permlane32_swap_b32_e32 v90, v95
	v_permlane32_swap_b32_e32 v28, v33
	v_permlane32_swap_b32_e32 v38, v43
	v_permlane32_swap_b32_e32 v6, v11
	v_add_f32_e32 v50, v50, v55
	v_add_f32_e32 v60, v60, v65
	v_add_f32_e32 v70, v70, v75
	v_add_f32_e32 v80, v80, v85
	v_add_f32_e32 v90, v90, v95
	v_add_f32_e32 v28, v28, v33
	v_add_f32_e32 v38, v38, v43
	v_add_f32_e32 v6, v6, v11
	s_and_saveexec_b64 s[12:13], s[10:11]
	s_cbranch_execz .Lmy_b2_done
;     ...
;           if (lane == 0 && hf == 0 && !(pm & 8)) {
;             const int n = n0 + step;
;             const int tok = dir ? (n < 256 ? 255 - n : 2559 - n) : n;
;             P.cbuf[((size_t)(dir * MALL + b * TALL + tok)) * 4 + hh] = cs;
;           }
;         }
;       }
;     }
	v_cmp_lt_i32_e32 vcc, s94, v130
	s_nop 1
	v_cndmask_b32_e32 v1, v219, v220, vcc
	v_add_u32_e32 v1, v147, v1
	v_mov_b32_e32 v46, v1
	v_add_u32_e32 v48, 0, v130
	v_cndmask_b32_e64 v46, v46, v48, s[4:5]
	v_add_u32_e32 v46, s87, v46
	v_ashrrev_i32_e32 v47, 31, v46
	v_lshl_add_u64 v[46:47], v[46:47], 4, s[2:3]
	global_store_dword v[46:47], v50, off
	v_subrev_u32_e32 v56, 1, v1
	v_add_u32_e32 v58, 1, v130
	v_cndmask_b32_e64 v56, v56, v58, s[4:5]
	v_add_u32_e32 v56, s87, v56
	v_ashrrev_i32_e32 v57, 31, v56
	v_lshl_add_u64 v[56:57], v[56:57], 4, s[2:3]
	global_store_dword v[56:57], v60, off
	v_subrev_u32_e32 v66, 2, v1
	v_add_u32_e32 v68, 2, v130
	v_cndmask_b32_e64 v66, v66, v68, s[4:5]
	v_add_u32_e32 v66, s87, v66
	v_ashrrev_i32_e32 v67, 31, v66
	v_lshl_add_u64 v[66:67], v[66:67], 4, s[2:3]
	global_store_dword v[66:67], v70, off
	v_subrev_u32_e32 v76, 3, v1
	v_add_u32_e32 v78, 3, v130
	v_cndmask_b32_e64 v76, v76, v78, s[4:5]
	v_add_u32_e32 v76, s87, v76
	v_ashrrev_i32_e32 v77, 31, v76
	v_lshl_add_u64 v[76:77], v[76:77], 4, s[2:3]
	global_store_dword v[76:77], v80, off
	v_subrev_u32_e32 v86, 4, v1
	v_add_u32_e32 v88, 4, v130
	v_cndmask_b32_e64 v86, v86, v88, s[4:5]
	v_add_u32_e32 v86, s87, v86
	v_ashrrev_i32_e32 v87, 31, v86
	v_lshl_add_u64 v[86:87], v[86:87], 4, s[2:3]
	global_store_dword v[86:87], v90, off
	v_subrev_u32_e32 v24, 5, v1
	v_add_u32_e32 v26, 5, v130
	v_cndmask_b32_e64 v24, v24, v26, s[4:5]
	v_add_u32_e32 v24, s87, v24
	v_ashrrev_i32_e32 v25, 31, v24
	v_lshl_add_u64 v[24:25], v[24:25], 4, s[2:3]
	global_store_dword v[24:25], v28, off
	v_subrev_u32_e32 v34, 6, v1
	v_add_u32_e32 v36, 6, v130
	v_cndmask_b32_e64 v34, v34, v36, s[4:5]
	v_add_u32_e32 v34, s87, v34
	v_ashrrev_i32_e32 v35, 31, v34
	v_lshl_add_u64 v[34:35], v[34:35], 4, s[2:3]
	global_store_dword v[34:35], v38, off
	v_subrev_u32_e32 v2, 7, v1
	v_add_u32_e32 v4, 7, v130
	v_cndmask_b32_e64 v2, v2, v4, s[4:5]
	v_add_u32_e32 v2, s87, v2
	v_ashrrev_i32_e32 v3, 31, v2
	v_lshl_add_u64 v[2:3], v[2:3], 4, s[2:3]
	global_store_dword v[2:3], v6, off
.Lmy_b2_done:
	s_or_b64 exec, exec, s[12:13]
	s_branch .LBB0_350
.Lmy_first_chunk:
	s_waitcnt vmcnt(0)
	s_branch .LBB0_365
